# v2 + K-loops: s_setprio flips deleted, satisfied post-barrier lgkmcnt(0) deleted, LDS-DMA pieces SGPR-base addressed (no VALU adds, ds_reads fill the m0 wait states)
# speedup vs baseline: 1.0071x; 1.0053x over previous
.LBB0_249:
	s_lshl_b32 s2, s87, 7
	s_add_u32 s12, s84, s2
	s_addc_u32 s13, s85, 0
	s_add_u32 s4, s12, 0x100
	s_addc_u32 s5, s13, 0
	s_and_b64 s[2:3], s[92:93], exec
	v_add_u32_e32 v140, s0, v1
	s_mul_i32 s2, s87, 0x188800
	ds_read_b128 v[148:151], v140
	ds_read_b128 v[152:155], v140 offset:256
	ds_read_b128 v[156:159], v140 offset:8192
	ds_read_b128 v[160:163], v140 offset:8448
	v_add_u32_e32 v140, s1, v1
	s_cselect_b32 s5, s5, s81
	s_cselect_b32 s4, s4, s80
	s_add_u32 s2, s88, s2
	ds_read_b128 v[164:167], v140
	ds_read_b128 v[168:171], v140 offset:256
	ds_read_b128 v[172:175], v140 offset:8192
	ds_read_b128 v[176:179], v140 offset:8448
	s_addc_u32 s3, s89, 0
	s_add_u32 s20, s2, 0x311000
	s_addc_u32 s21, s3, 0
	s_and_b64 s[2:3], s[92:93], exec
	s_cselect_b32 s92, s20, s86
	s_cselect_b32 s93, s21, s75
	s_add_u32 s94, s92, 0x188800
	s_addc_u32 s95, s93, 0
	s_add_u32 s98, s92, s10
	s_addc_u32 s99, s93, s11
	s_add_u32 s100, s4, s52
	s_addc_u32 s101, s5, s53
	s_add_u32 s2, s12, 0x104080
	s_addc_u32 s3, s13, 0
	s_add_i32 m0, s68, 0xc000
	ds_read_b128 v[180:183], v145
	ds_read_b128 v[184:187], v145 offset:1024
	ds_read_b128 v[188:191], v145 offset:2048
	ds_read_b128 v[192:195], v145 offset:3072
	ds_read_b128 v[196:199], v145 offset:4096
	ds_read_b128 v[200:203], v145 offset:5120
	ds_read_b128 v[204:207], v145 offset:6144
	global_load_lds_dwordx4 v130, s[2:3]
	s_add_i32 m0, s68, 0xe000
	ds_read_b128 v[208:211], v145 offset:7168
	global_load_lds_dwordx4 v134, s[2:3]
	s_waitcnt vmcnt(8)
	s_waitcnt lgkmcnt(0)
	s_barrier
	v_mfma_f32_16x16x32_bf16 v[126:129], v[148:151], v[180:183], v[126:129]
	v_mfma_f32_16x16x32_bf16 v[122:125], v[152:155], v[180:183], v[122:125]
	v_mfma_f32_16x16x32_bf16 v[118:121], v[148:151], v[188:191], v[118:121]
	v_mfma_f32_16x16x32_bf16 v[110:113], v[152:155], v[188:191], v[110:113]
	v_mfma_f32_16x16x32_bf16 v[102:105], v[148:151], v[196:199], v[102:105]
	v_mfma_f32_16x16x32_bf16 v[94:97], v[152:155], v[196:199], v[94:97]
	v_mfma_f32_16x16x32_bf16 v[86:89], v[148:151], v[204:207], v[86:89]
	v_mfma_f32_16x16x32_bf16 v[78:81], v[152:155], v[204:207], v[78:81]
	v_mfma_f32_16x16x32_bf16 v[126:129], v[156:159], v[184:187], v[126:129]
	v_mfma_f32_16x16x32_bf16 v[122:125], v[160:163], v[184:187], v[122:125]
	v_mfma_f32_16x16x32_bf16 v[118:121], v[156:159], v[192:195], v[118:121]
	v_mfma_f32_16x16x32_bf16 v[110:113], v[160:163], v[192:195], v[110:113]
	v_mfma_f32_16x16x32_bf16 v[102:105], v[156:159], v[200:203], v[102:105]
	v_mfma_f32_16x16x32_bf16 v[94:97], v[160:163], v[200:203], v[94:97]
	v_mfma_f32_16x16x32_bf16 v[86:89], v[156:159], v[208:211], v[86:89]
	v_mfma_f32_16x16x32_bf16 v[78:81], v[160:163], v[208:211], v[78:81]
	v_mfma_f32_16x16x32_bf16 v[114:117], v[164:167], v[180:183], v[114:117]
	v_mfma_f32_16x16x32_bf16 v[106:109], v[168:171], v[180:183], v[106:109]
	v_mfma_f32_16x16x32_bf16 v[98:101], v[164:167], v[188:191], v[98:101]
	v_mfma_f32_16x16x32_bf16 v[90:93], v[168:171], v[188:191], v[90:93]
	v_mfma_f32_16x16x32_bf16 v[82:85], v[164:167], v[196:199], v[82:85]
	v_mfma_f32_16x16x32_bf16 v[74:77], v[168:171], v[196:199], v[74:77]
	v_mfma_f32_16x16x32_bf16 v[70:73], v[164:167], v[204:207], v[70:73]
	v_mfma_f32_16x16x32_bf16 v[66:69], v[168:171], v[204:207], v[66:69]
	v_mfma_f32_16x16x32_bf16 v[114:117], v[172:175], v[184:187], v[114:117]
	v_mfma_f32_16x16x32_bf16 v[106:109], v[176:179], v[184:187], v[106:109]
	v_mfma_f32_16x16x32_bf16 v[98:101], v[172:175], v[192:195], v[98:101]
	v_mfma_f32_16x16x32_bf16 v[90:93], v[176:179], v[192:195], v[90:93]
	v_mfma_f32_16x16x32_bf16 v[82:85], v[172:175], v[200:203], v[82:85]
	v_mfma_f32_16x16x32_bf16 v[74:77], v[176:179], v[200:203], v[74:77]
	v_mfma_f32_16x16x32_bf16 v[70:73], v[172:175], v[208:211], v[70:73]
	v_mfma_f32_16x16x32_bf16 v[66:69], v[176:179], v[208:211], v[66:69]
	s_barrier
	s_add_i32 s2, s0, s15
	s_mov_b32 m0, s2
	ds_read_b128 v[180:183], v145 offset:16384
	ds_read_b128 v[184:187], v145 offset:17408
	ds_read_b128 v[188:191], v145 offset:18432
	ds_read_b128 v[192:195], v145 offset:19456
	global_load_lds_dwordx4 v132, s[92:93]
	s_add_i32 m0, s2, 0x2000
	s_add_i32 s2, s1, s15
	global_load_lds_dwordx4 v136, s[92:93]
	s_mov_b32 m0, s2
	ds_read_b128 v[196:199], v145 offset:20480
	global_load_lds_dwordx4 v132, s[98:99]
	s_add_i32 m0, s2, 0x2000
	ds_read_b128 v[200:203], v145 offset:21504
	global_load_lds_dwordx4 v136, s[98:99]
	s_mov_b32 m0, s68
	ds_read_b128 v[204:207], v145 offset:22528
	global_load_lds_dwordx4 v130, s[4:5]
	s_mov_b32 m0, s69
	ds_read_b128 v[208:211], v145 offset:23552
	global_load_lds_dwordx4 v134, s[4:5]
	s_waitcnt vmcnt(8)
	s_waitcnt lgkmcnt(0)
	s_barrier
	v_mfma_f32_16x16x32_bf16 v[62:65], v[148:151], v[180:183], v[62:65]
	v_mfma_f32_16x16x32_bf16 v[58:61], v[152:155], v[180:183], v[58:61]
	v_mfma_f32_16x16x32_bf16 v[54:57], v[148:151], v[188:191], v[54:57]
	v_mfma_f32_16x16x32_bf16 v[46:49], v[152:155], v[188:191], v[46:49]
	v_mfma_f32_16x16x32_bf16 v[38:41], v[148:151], v[196:199], v[38:41]
	v_mfma_f32_16x16x32_bf16 v[30:33], v[152:155], v[196:199], v[30:33]
	v_mfma_f32_16x16x32_bf16 v[22:25], v[148:151], v[204:207], v[22:25]
	v_mfma_f32_16x16x32_bf16 v[14:17], v[152:155], v[204:207], v[14:17]
	v_mfma_f32_16x16x32_bf16 v[62:65], v[156:159], v[184:187], v[62:65]
	v_mfma_f32_16x16x32_bf16 v[58:61], v[160:163], v[184:187], v[58:61]
	v_mfma_f32_16x16x32_bf16 v[54:57], v[156:159], v[192:195], v[54:57]
	v_mfma_f32_16x16x32_bf16 v[46:49], v[160:163], v[192:195], v[46:49]
	v_mfma_f32_16x16x32_bf16 v[38:41], v[156:159], v[200:203], v[38:41]
	v_mfma_f32_16x16x32_bf16 v[30:33], v[160:163], v[200:203], v[30:33]
	v_mfma_f32_16x16x32_bf16 v[22:25], v[156:159], v[208:211], v[22:25]
	v_mfma_f32_16x16x32_bf16 v[14:17], v[160:163], v[208:211], v[14:17]
	v_mfma_f32_16x16x32_bf16 v[50:53], v[164:167], v[180:183], v[50:53]
	v_mfma_f32_16x16x32_bf16 v[42:45], v[168:171], v[180:183], v[42:45]
	v_mfma_f32_16x16x32_bf16 v[34:37], v[164:167], v[188:191], v[34:37]
	v_mfma_f32_16x16x32_bf16 v[26:29], v[168:171], v[188:191], v[26:29]
	v_mfma_f32_16x16x32_bf16 v[18:21], v[164:167], v[196:199], v[18:21]
	v_mfma_f32_16x16x32_bf16 v[10:13], v[168:171], v[196:199], v[10:13]
	v_mfma_f32_16x16x32_bf16 v[6:9], v[164:167], v[204:207], v[6:9]
	v_mfma_f32_16x16x32_bf16 v[2:5], v[168:171], v[204:207], v[2:5]
	v_mfma_f32_16x16x32_bf16 v[50:53], v[172:175], v[184:187], v[50:53]
	v_mfma_f32_16x16x32_bf16 v[42:45], v[176:179], v[184:187], v[42:45]
	v_mfma_f32_16x16x32_bf16 v[34:37], v[172:175], v[192:195], v[34:37]
	v_mfma_f32_16x16x32_bf16 v[26:29], v[176:179], v[192:195], v[26:29]
	v_mfma_f32_16x16x32_bf16 v[18:21], v[172:175], v[200:203], v[18:21]
	v_mfma_f32_16x16x32_bf16 v[10:13], v[176:179], v[200:203], v[10:13]
	v_mfma_f32_16x16x32_bf16 v[6:9], v[172:175], v[208:211], v[6:9]
	v_mfma_f32_16x16x32_bf16 v[2:5], v[176:179], v[208:211], v[2:5]
	s_barrier
	s_add_i32 s12, 0, 0x18000
	v_add_u32_e32 v147, s12, v1
	s_add_i32 s13, 0, 0x1c000
	ds_read_b128 v[148:151], v147
	ds_read_b128 v[152:155], v147 offset:256
	ds_read_b128 v[156:159], v147 offset:8192
	ds_read_b128 v[160:163], v147 offset:8448
	v_add_u32_e32 v147, s13, v1
	ds_read_b128 v[164:167], v147
	ds_read_b128 v[168:171], v147 offset:256
	ds_read_b128 v[172:175], v147 offset:8192
	ds_read_b128 v[176:179], v147 offset:8448
	s_add_u32 s2, s4, 0x104000
	s_addc_u32 s3, s5, 0
	s_mov_b32 m0, s70
	ds_read_b128 v[180:183], v145 offset:32768
	ds_read_b128 v[184:187], v145 offset:33792
	ds_read_b128 v[188:191], v145 offset:34816
	ds_read_b128 v[192:195], v145 offset:35840
	ds_read_b128 v[196:199], v145 offset:36864
	ds_read_b128 v[200:203], v145 offset:37888
	ds_read_b128 v[204:207], v145 offset:38912
	global_load_lds_dwordx4 v130, s[2:3]
	s_mov_b32 m0, s71
	ds_read_b128 v[208:211], v145 offset:39936
	global_load_lds_dwordx4 v134, s[2:3]
	s_waitcnt vmcnt(8)
	s_waitcnt lgkmcnt(0)
	s_barrier
	v_mfma_f32_16x16x32_bf16 v[126:129], v[148:151], v[180:183], v[126:129]
	v_mfma_f32_16x16x32_bf16 v[122:125], v[152:155], v[180:183], v[122:125]
	v_mfma_f32_16x16x32_bf16 v[118:121], v[148:151], v[188:191], v[118:121]
	v_mfma_f32_16x16x32_bf16 v[110:113], v[152:155], v[188:191], v[110:113]
	v_mfma_f32_16x16x32_bf16 v[102:105], v[148:151], v[196:199], v[102:105]
	v_mfma_f32_16x16x32_bf16 v[94:97], v[152:155], v[196:199], v[94:97]
	v_mfma_f32_16x16x32_bf16 v[86:89], v[148:151], v[204:207], v[86:89]
	v_mfma_f32_16x16x32_bf16 v[78:81], v[152:155], v[204:207], v[78:81]
	v_mfma_f32_16x16x32_bf16 v[126:129], v[156:159], v[184:187], v[126:129]
	v_mfma_f32_16x16x32_bf16 v[122:125], v[160:163], v[184:187], v[122:125]
	v_mfma_f32_16x16x32_bf16 v[118:121], v[156:159], v[192:195], v[118:121]
	v_mfma_f32_16x16x32_bf16 v[110:113], v[160:163], v[192:195], v[110:113]
	v_mfma_f32_16x16x32_bf16 v[102:105], v[156:159], v[200:203], v[102:105]
	v_mfma_f32_16x16x32_bf16 v[94:97], v[160:163], v[200:203], v[94:97]
	v_mfma_f32_16x16x32_bf16 v[86:89], v[156:159], v[208:211], v[86:89]
	v_mfma_f32_16x16x32_bf16 v[78:81], v[160:163], v[208:211], v[78:81]
	v_mfma_f32_16x16x32_bf16 v[114:117], v[164:167], v[180:183], v[114:117]
	v_mfma_f32_16x16x32_bf16 v[106:109], v[168:171], v[180:183], v[106:109]
	v_mfma_f32_16x16x32_bf16 v[98:101], v[164:167], v[188:191], v[98:101]
	v_mfma_f32_16x16x32_bf16 v[90:93], v[168:171], v[188:191], v[90:93]
	v_mfma_f32_16x16x32_bf16 v[82:85], v[164:167], v[196:199], v[82:85]
	v_mfma_f32_16x16x32_bf16 v[74:77], v[168:171], v[196:199], v[74:77]
	v_mfma_f32_16x16x32_bf16 v[70:73], v[164:167], v[204:207], v[70:73]
	v_mfma_f32_16x16x32_bf16 v[66:69], v[168:171], v[204:207], v[66:69]
	v_mfma_f32_16x16x32_bf16 v[114:117], v[172:175], v[184:187], v[114:117]
	v_mfma_f32_16x16x32_bf16 v[106:109], v[176:179], v[184:187], v[106:109]
	v_mfma_f32_16x16x32_bf16 v[98:101], v[172:175], v[192:195], v[98:101]
	v_mfma_f32_16x16x32_bf16 v[90:93], v[176:179], v[192:195], v[90:93]
	v_mfma_f32_16x16x32_bf16 v[82:85], v[172:175], v[200:203], v[82:85]
	v_mfma_f32_16x16x32_bf16 v[74:77], v[176:179], v[200:203], v[74:77]
	v_mfma_f32_16x16x32_bf16 v[70:73], v[172:175], v[208:211], v[70:73]
	v_mfma_f32_16x16x32_bf16 v[66:69], v[176:179], v[208:211], v[66:69]
	s_barrier
	s_add_i32 s2, s12, s15
	s_mov_b32 m0, s2
	ds_read_b128 v[180:183], v145 offset:49152
	ds_read_b128 v[184:187], v145 offset:50176
	ds_read_b128 v[188:191], v145 offset:51200
	ds_read_b128 v[192:195], v145 offset:52224
	global_load_lds_dwordx4 v132, s[94:95]
	s_add_i32 m0, s2, 0x2000
	s_add_u32 s2, s92, 0x189000
	s_addc_u32 s3, s93, 0
	s_add_i32 s4, s13, s15
	global_load_lds_dwordx4 v136, s[94:95]
	s_mov_b32 m0, s4
	ds_read_b128 v[196:199], v145 offset:53248
	global_load_lds_dwordx4 v132, s[2:3]
	s_add_i32 m0, s4, 0x2000
	ds_read_b128 v[200:203], v145 offset:54272
	global_load_lds_dwordx4 v136, s[2:3]
	s_mov_b32 m0, s8
	ds_read_b128 v[204:207], v145 offset:55296
	global_load_lds_dwordx4 v130, s[100:101]
	s_mov_b32 m0, s9
	ds_read_b128 v[208:211], v145 offset:56320
	global_load_lds_dwordx4 v134, s[100:101]
	s_waitcnt vmcnt(8)
	s_waitcnt lgkmcnt(0)
	s_barrier
	v_mfma_f32_16x16x32_bf16 v[62:65], v[148:151], v[180:183], v[62:65]
	v_mfma_f32_16x16x32_bf16 v[58:61], v[152:155], v[180:183], v[58:61]
	v_mfma_f32_16x16x32_bf16 v[54:57], v[148:151], v[188:191], v[54:57]
	v_mfma_f32_16x16x32_bf16 v[46:49], v[152:155], v[188:191], v[46:49]
	v_mfma_f32_16x16x32_bf16 v[38:41], v[148:151], v[196:199], v[38:41]
	v_mfma_f32_16x16x32_bf16 v[30:33], v[152:155], v[196:199], v[30:33]
	v_mfma_f32_16x16x32_bf16 v[22:25], v[148:151], v[204:207], v[22:25]
	v_mfma_f32_16x16x32_bf16 v[14:17], v[152:155], v[204:207], v[14:17]
	v_mfma_f32_16x16x32_bf16 v[62:65], v[156:159], v[184:187], v[62:65]
	v_mfma_f32_16x16x32_bf16 v[58:61], v[160:163], v[184:187], v[58:61]
	v_mfma_f32_16x16x32_bf16 v[54:57], v[156:159], v[192:195], v[54:57]
	v_mfma_f32_16x16x32_bf16 v[46:49], v[160:163], v[192:195], v[46:49]
	v_mfma_f32_16x16x32_bf16 v[38:41], v[156:159], v[200:203], v[38:41]
	v_mfma_f32_16x16x32_bf16 v[30:33], v[160:163], v[200:203], v[30:33]
	v_mfma_f32_16x16x32_bf16 v[22:25], v[156:159], v[208:211], v[22:25]
	v_mfma_f32_16x16x32_bf16 v[14:17], v[160:163], v[208:211], v[14:17]
	v_mfma_f32_16x16x32_bf16 v[50:53], v[164:167], v[180:183], v[50:53]
	v_mfma_f32_16x16x32_bf16 v[42:45], v[168:171], v[180:183], v[42:45]
	v_mfma_f32_16x16x32_bf16 v[34:37], v[164:167], v[188:191], v[34:37]
	v_mfma_f32_16x16x32_bf16 v[26:29], v[168:171], v[188:191], v[26:29]
	v_mfma_f32_16x16x32_bf16 v[18:21], v[164:167], v[196:199], v[18:21]
	v_mfma_f32_16x16x32_bf16 v[10:13], v[168:171], v[196:199], v[10:13]
	v_mfma_f32_16x16x32_bf16 v[6:9], v[164:167], v[204:207], v[6:9]
	v_mfma_f32_16x16x32_bf16 v[2:5], v[168:171], v[204:207], v[2:5]
	v_mfma_f32_16x16x32_bf16 v[50:53], v[172:175], v[184:187], v[50:53]
	v_mfma_f32_16x16x32_bf16 v[42:45], v[176:179], v[184:187], v[42:45]
	v_mfma_f32_16x16x32_bf16 v[34:37], v[172:175], v[192:195], v[34:37]
	v_mfma_f32_16x16x32_bf16 v[26:29], v[176:179], v[192:195], v[26:29]
	v_mfma_f32_16x16x32_bf16 v[18:21], v[172:175], v[200:203], v[18:21]
	v_mfma_f32_16x16x32_bf16 v[10:13], v[176:179], v[200:203], v[10:13]
	v_mfma_f32_16x16x32_bf16 v[6:9], v[172:175], v[208:211], v[6:9]
	v_mfma_f32_16x16x32_bf16 v[2:5], v[176:179], v[208:211], v[2:5]
	s_barrier
	s_add_i32 s2, s87, 2
	s_cmp_gt_u32 s87, 61
	s_cbranch_scc1 .LBB0_255
	s_mov_b32 s87, s2
	s_branch .LBB0_220

.LBB0_558:
	s_lshl_b32 s2, s69, 7
	s_add_u32 s20, s74, s2
	s_addc_u32 s21, s75, 0
	s_add_u32 s4, s20, 0x100
	s_addc_u32 s5, s21, 0
	s_and_b64 s[2:3], s[82:83], exec
	s_mul_i32 s2, s69, 0x88800
	v_add_u32_e32 v188, s93, v1
	v_add_u32_e32 v204, s18, v1
	s_cselect_b32 s5, s5, s63
	s_cselect_b32 s4, s4, s62
	s_add_u32 s2, s78, s2
	ds_read_b128 v[130:133], v188
	ds_read_b128 v[134:137], v188 offset:256
	ds_read_b128 v[180:183], v188 offset:8192
	ds_read_b128 v[188:191], v188 offset:8448
	ds_read_b128 v[192:195], v204
	ds_read_b128 v[196:199], v204 offset:256
	ds_read_b128 v[200:203], v204 offset:8192
	ds_read_b128 v[204:207], v204 offset:8448
	s_addc_u32 s3, s79, 0
	s_add_u32 s22, s2, 0x111000
	s_addc_u32 s23, s3, 0
	s_and_b64 s[2:3], s[82:83], exec
	s_cselect_b32 s82, s22, s61
	s_cselect_b32 s83, s23, s14
	s_add_u32 s84, s82, 0x88800
	s_addc_u32 s85, s83, 0
	s_add_u32 s98, s82, s12
	s_addc_u32 s99, s83, s13
	s_add_u32 s100, s4, s56
	s_addc_u32 s101, s5, s57
	s_add_u32 s2, s20, 0x104080
	s_addc_u32 s3, s21, 0
	s_add_i32 m0, s94, 0xc000
	ds_read_b128 v[208:211], v186
	ds_read_b128 v[212:215], v186 offset:1024
	ds_read_b128 v[216:219], v186 offset:2048
	ds_read_b128 v[220:223], v186 offset:3072
	ds_read_b128 v[224:227], v186 offset:4096
	ds_read_b128 v[228:231], v186 offset:5120
	ds_read_b128 v[232:235], v186 offset:6144
	global_load_lds_dwordx4 v138, s[2:3]
	s_add_i32 m0, s94, 0xe000
	ds_read_b128 v[236:239], v186 offset:7168
	global_load_lds_dwordx4 v142, s[2:3]
	s_waitcnt vmcnt(8)
	s_waitcnt lgkmcnt(0)
	s_barrier
	v_mfma_f32_16x16x32_bf16 v[126:129], v[130:133], v[208:211], v[126:129]
	v_mfma_f32_16x16x32_bf16 v[122:125], v[134:137], v[208:211], v[122:125]
	v_mfma_f32_16x16x32_bf16 v[110:113], v[130:133], v[216:219], v[110:113]
	v_mfma_f32_16x16x32_bf16 v[106:109], v[134:137], v[216:219], v[106:109]
	v_mfma_f32_16x16x32_bf16 v[94:97], v[130:133], v[224:227], v[94:97]
	v_mfma_f32_16x16x32_bf16 v[90:93], v[134:137], v[224:227], v[90:93]
	v_mfma_f32_16x16x32_bf16 v[78:81], v[130:133], v[232:235], v[78:81]
	v_mfma_f32_16x16x32_bf16 v[74:77], v[134:137], v[232:235], v[74:77]
	v_mfma_f32_16x16x32_bf16 v[126:129], v[180:183], v[212:215], v[126:129]
	v_mfma_f32_16x16x32_bf16 v[122:125], v[188:191], v[212:215], v[122:125]
	v_mfma_f32_16x16x32_bf16 v[110:113], v[180:183], v[220:223], v[110:113]
	v_mfma_f32_16x16x32_bf16 v[106:109], v[188:191], v[220:223], v[106:109]
	v_mfma_f32_16x16x32_bf16 v[94:97], v[180:183], v[228:231], v[94:97]
	v_mfma_f32_16x16x32_bf16 v[90:93], v[188:191], v[228:231], v[90:93]
	v_mfma_f32_16x16x32_bf16 v[78:81], v[180:183], v[236:239], v[78:81]
	v_mfma_f32_16x16x32_bf16 v[74:77], v[188:191], v[236:239], v[74:77]
	v_mfma_f32_16x16x32_bf16 v[118:121], v[192:195], v[208:211], v[118:121]
	v_mfma_f32_16x16x32_bf16 v[114:117], v[196:199], v[208:211], v[114:117]
	v_mfma_f32_16x16x32_bf16 v[102:105], v[192:195], v[216:219], v[102:105]
	v_mfma_f32_16x16x32_bf16 v[98:101], v[196:199], v[216:219], v[98:101]
	v_mfma_f32_16x16x32_bf16 v[86:89], v[192:195], v[224:227], v[86:89]
	v_mfma_f32_16x16x32_bf16 v[82:85], v[196:199], v[224:227], v[82:85]
	v_mfma_f32_16x16x32_bf16 v[70:73], v[192:195], v[232:235], v[70:73]
	v_mfma_f32_16x16x32_bf16 v[66:69], v[196:199], v[232:235], v[66:69]
	v_mfma_f32_16x16x32_bf16 v[118:121], v[200:203], v[212:215], v[118:121]
	v_mfma_f32_16x16x32_bf16 v[114:117], v[204:207], v[212:215], v[114:117]
	v_mfma_f32_16x16x32_bf16 v[102:105], v[200:203], v[220:223], v[102:105]
	v_mfma_f32_16x16x32_bf16 v[98:101], v[204:207], v[220:223], v[98:101]
	v_mfma_f32_16x16x32_bf16 v[86:89], v[200:203], v[228:231], v[86:89]
	v_mfma_f32_16x16x32_bf16 v[82:85], v[204:207], v[228:231], v[82:85]
	v_mfma_f32_16x16x32_bf16 v[70:73], v[200:203], v[236:239], v[70:73]
	v_mfma_f32_16x16x32_bf16 v[66:69], v[204:207], v[236:239], v[66:69]
	s_barrier
	s_add_i32 s2, s93, s73
	s_mov_b32 m0, s2
	ds_read_b128 v[208:211], v186 offset:16384
	ds_read_b128 v[212:215], v186 offset:17408
	ds_read_b128 v[216:219], v186 offset:18432
	ds_read_b128 v[220:223], v186 offset:19456
	global_load_lds_dwordx4 v140, s[82:83]
	s_add_i32 m0, s2, 0x2000
	s_add_i32 s2, s18, s73
	global_load_lds_dwordx4 v144, s[82:83]
	s_mov_b32 m0, s2
	ds_read_b128 v[224:227], v186 offset:20480
	global_load_lds_dwordx4 v140, s[98:99]
	s_add_i32 m0, s2, 0x2000
	ds_read_b128 v[228:231], v186 offset:21504
	global_load_lds_dwordx4 v144, s[98:99]
	s_mov_b32 m0, s94
	ds_read_b128 v[232:235], v186 offset:22528
	global_load_lds_dwordx4 v138, s[4:5]
	s_mov_b32 m0, s95
	ds_read_b128 v[236:239], v186 offset:23552
	global_load_lds_dwordx4 v142, s[4:5]
	s_waitcnt vmcnt(8)
	s_waitcnt lgkmcnt(0)
	s_barrier
	v_mfma_f32_16x16x32_bf16 v[62:65], v[130:133], v[208:211], v[62:65]
	v_mfma_f32_16x16x32_bf16 v[58:61], v[134:137], v[208:211], v[58:61]
	v_mfma_f32_16x16x32_bf16 v[46:49], v[130:133], v[216:219], v[46:49]
	v_mfma_f32_16x16x32_bf16 v[42:45], v[134:137], v[216:219], v[42:45]
	v_mfma_f32_16x16x32_bf16 v[30:33], v[130:133], v[224:227], v[30:33]
	v_mfma_f32_16x16x32_bf16 v[26:29], v[134:137], v[224:227], v[26:29]
	v_mfma_f32_16x16x32_bf16 v[14:17], v[130:133], v[232:235], v[14:17]
	v_mfma_f32_16x16x32_bf16 v[10:13], v[134:137], v[232:235], v[10:13]
	v_mfma_f32_16x16x32_bf16 v[62:65], v[180:183], v[212:215], v[62:65]
	v_mfma_f32_16x16x32_bf16 v[58:61], v[188:191], v[212:215], v[58:61]
	v_mfma_f32_16x16x32_bf16 v[46:49], v[180:183], v[220:223], v[46:49]
	v_mfma_f32_16x16x32_bf16 v[42:45], v[188:191], v[220:223], v[42:45]
	v_mfma_f32_16x16x32_bf16 v[30:33], v[180:183], v[228:231], v[30:33]
	v_mfma_f32_16x16x32_bf16 v[26:29], v[188:191], v[228:231], v[26:29]
	v_mfma_f32_16x16x32_bf16 v[14:17], v[180:183], v[236:239], v[14:17]
	v_mfma_f32_16x16x32_bf16 v[10:13], v[188:191], v[236:239], v[10:13]
	v_mfma_f32_16x16x32_bf16 v[54:57], v[192:195], v[208:211], v[54:57]
	v_mfma_f32_16x16x32_bf16 v[50:53], v[196:199], v[208:211], v[50:53]
	v_mfma_f32_16x16x32_bf16 v[38:41], v[192:195], v[216:219], v[38:41]
	v_mfma_f32_16x16x32_bf16 v[34:37], v[196:199], v[216:219], v[34:37]
	v_mfma_f32_16x16x32_bf16 v[22:25], v[192:195], v[224:227], v[22:25]
	v_mfma_f32_16x16x32_bf16 v[18:21], v[196:199], v[224:227], v[18:21]
	v_mfma_f32_16x16x32_bf16 v[6:9], v[192:195], v[232:235], v[6:9]
	v_mfma_f32_16x16x32_bf16 v[2:5], v[196:199], v[232:235], v[2:5]
	v_mfma_f32_16x16x32_bf16 v[54:57], v[200:203], v[212:215], v[54:57]
	v_mfma_f32_16x16x32_bf16 v[50:53], v[204:207], v[212:215], v[50:53]
	v_mfma_f32_16x16x32_bf16 v[38:41], v[200:203], v[220:223], v[38:41]
	v_mfma_f32_16x16x32_bf16 v[34:37], v[204:207], v[220:223], v[34:37]
	v_mfma_f32_16x16x32_bf16 v[22:25], v[200:203], v[228:231], v[22:25]
	v_mfma_f32_16x16x32_bf16 v[18:21], v[204:207], v[228:231], v[18:21]
	v_mfma_f32_16x16x32_bf16 v[6:9], v[200:203], v[236:239], v[6:9]
	v_mfma_f32_16x16x32_bf16 v[2:5], v[204:207], v[236:239], v[2:5]
	s_barrier
	s_add_i32 s20, 0, 0x18000
	s_add_i32 s21, 0, 0x1c000
	v_add_u32_e32 v188, s20, v1
	v_add_u32_e32 v204, s21, v1
	ds_read_b128 v[130:133], v188
	ds_read_b128 v[134:137], v188 offset:256
	ds_read_b128 v[180:183], v188 offset:8192
	ds_read_b128 v[188:191], v188 offset:8448
	ds_read_b128 v[192:195], v204
	ds_read_b128 v[196:199], v204 offset:256
	ds_read_b128 v[200:203], v204 offset:8192
	ds_read_b128 v[204:207], v204 offset:8448
	s_add_u32 s2, s4, 0x104000
	s_addc_u32 s3, s5, 0
	s_mov_b32 m0, s96
	ds_read_b128 v[208:211], v186 offset:32768
	ds_read_b128 v[212:215], v186 offset:33792
	ds_read_b128 v[216:219], v186 offset:34816
	ds_read_b128 v[220:223], v186 offset:35840
	ds_read_b128 v[224:227], v186 offset:36864
	ds_read_b128 v[228:231], v186 offset:37888
	ds_read_b128 v[232:235], v186 offset:38912
	global_load_lds_dwordx4 v138, s[2:3]
	s_mov_b32 m0, s97
	ds_read_b128 v[236:239], v186 offset:39936
	global_load_lds_dwordx4 v142, s[2:3]
	s_waitcnt vmcnt(8)
	s_waitcnt lgkmcnt(0)
	s_barrier
	v_mfma_f32_16x16x32_bf16 v[126:129], v[130:133], v[208:211], v[126:129]
	v_mfma_f32_16x16x32_bf16 v[122:125], v[134:137], v[208:211], v[122:125]
	v_mfma_f32_16x16x32_bf16 v[110:113], v[130:133], v[216:219], v[110:113]
	v_mfma_f32_16x16x32_bf16 v[106:109], v[134:137], v[216:219], v[106:109]
	v_mfma_f32_16x16x32_bf16 v[94:97], v[130:133], v[224:227], v[94:97]
	v_mfma_f32_16x16x32_bf16 v[90:93], v[134:137], v[224:227], v[90:93]
	v_mfma_f32_16x16x32_bf16 v[78:81], v[130:133], v[232:235], v[78:81]
	v_mfma_f32_16x16x32_bf16 v[74:77], v[134:137], v[232:235], v[74:77]
	v_mfma_f32_16x16x32_bf16 v[126:129], v[180:183], v[212:215], v[126:129]
	v_mfma_f32_16x16x32_bf16 v[122:125], v[188:191], v[212:215], v[122:125]
	v_mfma_f32_16x16x32_bf16 v[110:113], v[180:183], v[220:223], v[110:113]
	v_mfma_f32_16x16x32_bf16 v[106:109], v[188:191], v[220:223], v[106:109]
	v_mfma_f32_16x16x32_bf16 v[94:97], v[180:183], v[228:231], v[94:97]
	v_mfma_f32_16x16x32_bf16 v[90:93], v[188:191], v[228:231], v[90:93]
	v_mfma_f32_16x16x32_bf16 v[78:81], v[180:183], v[236:239], v[78:81]
	v_mfma_f32_16x16x32_bf16 v[74:77], v[188:191], v[236:239], v[74:77]
	v_mfma_f32_16x16x32_bf16 v[118:121], v[192:195], v[208:211], v[118:121]
	v_mfma_f32_16x16x32_bf16 v[114:117], v[196:199], v[208:211], v[114:117]
	v_mfma_f32_16x16x32_bf16 v[102:105], v[192:195], v[216:219], v[102:105]
	v_mfma_f32_16x16x32_bf16 v[98:101], v[196:199], v[216:219], v[98:101]
	v_mfma_f32_16x16x32_bf16 v[86:89], v[192:195], v[224:227], v[86:89]
	v_mfma_f32_16x16x32_bf16 v[82:85], v[196:199], v[224:227], v[82:85]
	v_mfma_f32_16x16x32_bf16 v[70:73], v[192:195], v[232:235], v[70:73]
	v_mfma_f32_16x16x32_bf16 v[66:69], v[196:199], v[232:235], v[66:69]
	v_mfma_f32_16x16x32_bf16 v[118:121], v[200:203], v[212:215], v[118:121]
	v_mfma_f32_16x16x32_bf16 v[114:117], v[204:207], v[212:215], v[114:117]
	v_mfma_f32_16x16x32_bf16 v[102:105], v[200:203], v[220:223], v[102:105]
	v_mfma_f32_16x16x32_bf16 v[98:101], v[204:207], v[220:223], v[98:101]
	v_mfma_f32_16x16x32_bf16 v[86:89], v[200:203], v[228:231], v[86:89]
	v_mfma_f32_16x16x32_bf16 v[82:85], v[204:207], v[228:231], v[82:85]
	v_mfma_f32_16x16x32_bf16 v[70:73], v[200:203], v[236:239], v[70:73]
	v_mfma_f32_16x16x32_bf16 v[66:69], v[204:207], v[236:239], v[66:69]
	s_barrier
	s_add_i32 s2, s20, s73
	s_mov_b32 m0, s2
	ds_read_b128 v[208:211], v186 offset:49152
	ds_read_b128 v[212:215], v186 offset:50176
	ds_read_b128 v[216:219], v186 offset:51200
	ds_read_b128 v[220:223], v186 offset:52224
	global_load_lds_dwordx4 v140, s[84:85]
	s_add_i32 m0, s2, 0x2000
	s_add_u32 s2, s82, 0x89000
	s_addc_u32 s3, s83, 0
	s_add_i32 s4, s21, s73
	global_load_lds_dwordx4 v144, s[84:85]
	s_mov_b32 m0, s4
	ds_read_b128 v[224:227], v186 offset:53248
	global_load_lds_dwordx4 v140, s[2:3]
	s_add_i32 m0, s4, 0x2000
	ds_read_b128 v[228:231], v186 offset:54272
	global_load_lds_dwordx4 v144, s[2:3]
	s_mov_b32 m0, s53
	ds_read_b128 v[232:235], v186 offset:55296
	global_load_lds_dwordx4 v138, s[100:101]
	s_mov_b32 m0, s92
	ds_read_b128 v[236:239], v186 offset:56320
	global_load_lds_dwordx4 v142, s[100:101]
	s_waitcnt vmcnt(8)
	s_waitcnt lgkmcnt(0)
	s_barrier
	v_mfma_f32_16x16x32_bf16 v[62:65], v[130:133], v[208:211], v[62:65]
	v_mfma_f32_16x16x32_bf16 v[58:61], v[134:137], v[208:211], v[58:61]
	v_mfma_f32_16x16x32_bf16 v[46:49], v[130:133], v[216:219], v[46:49]
	v_mfma_f32_16x16x32_bf16 v[42:45], v[134:137], v[216:219], v[42:45]
	v_mfma_f32_16x16x32_bf16 v[30:33], v[130:133], v[224:227], v[30:33]
	v_mfma_f32_16x16x32_bf16 v[26:29], v[134:137], v[224:227], v[26:29]
	v_mfma_f32_16x16x32_bf16 v[14:17], v[130:133], v[232:235], v[14:17]
	v_mfma_f32_16x16x32_bf16 v[10:13], v[134:137], v[232:235], v[10:13]
	v_mfma_f32_16x16x32_bf16 v[62:65], v[180:183], v[212:215], v[62:65]
	v_mfma_f32_16x16x32_bf16 v[58:61], v[188:191], v[212:215], v[58:61]
	v_mfma_f32_16x16x32_bf16 v[46:49], v[180:183], v[220:223], v[46:49]
	v_mfma_f32_16x16x32_bf16 v[42:45], v[188:191], v[220:223], v[42:45]
	v_mfma_f32_16x16x32_bf16 v[30:33], v[180:183], v[228:231], v[30:33]
	v_mfma_f32_16x16x32_bf16 v[26:29], v[188:191], v[228:231], v[26:29]
	v_mfma_f32_16x16x32_bf16 v[14:17], v[180:183], v[236:239], v[14:17]
	v_mfma_f32_16x16x32_bf16 v[10:13], v[188:191], v[236:239], v[10:13]
	v_mfma_f32_16x16x32_bf16 v[54:57], v[192:195], v[208:211], v[54:57]
	v_mfma_f32_16x16x32_bf16 v[50:53], v[196:199], v[208:211], v[50:53]
	v_mfma_f32_16x16x32_bf16 v[38:41], v[192:195], v[216:219], v[38:41]
	v_mfma_f32_16x16x32_bf16 v[34:37], v[196:199], v[216:219], v[34:37]
	v_mfma_f32_16x16x32_bf16 v[22:25], v[192:195], v[224:227], v[22:25]
	v_mfma_f32_16x16x32_bf16 v[18:21], v[196:199], v[224:227], v[18:21]
	v_mfma_f32_16x16x32_bf16 v[6:9], v[192:195], v[232:235], v[6:9]
	v_mfma_f32_16x16x32_bf16 v[2:5], v[196:199], v[232:235], v[2:5]
	v_mfma_f32_16x16x32_bf16 v[54:57], v[200:203], v[212:215], v[54:57]
	v_mfma_f32_16x16x32_bf16 v[50:53], v[204:207], v[212:215], v[50:53]
	v_mfma_f32_16x16x32_bf16 v[38:41], v[200:203], v[220:223], v[38:41]
	v_mfma_f32_16x16x32_bf16 v[34:37], v[204:207], v[220:223], v[34:37]
	v_mfma_f32_16x16x32_bf16 v[22:25], v[200:203], v[228:231], v[22:25]
	v_mfma_f32_16x16x32_bf16 v[18:21], v[204:207], v[228:231], v[18:21]
	v_mfma_f32_16x16x32_bf16 v[6:9], v[200:203], v[236:239], v[6:9]
	v_mfma_f32_16x16x32_bf16 v[2:5], v[204:207], v[236:239], v[2:5]
	s_barrier
	s_add_i32 s2, s69, 2
	s_cmp_gt_u32 s69, 61
	s_cbranch_scc1 .LBB0_564
	s_mov_b32 s69, s2
	s_branch .LBB0_529

.LBB0_796:
	s_lshl_b32 s2, s90, 7
	s_add_u32 s20, s54, s2
	s_addc_u32 s21, s55, 0
	s_add_u32 s4, s20, 0x100
	s_addc_u32 s5, s21, 0
	s_and_b64 s[2:3], s[60:61], exec
	v_add_u32_e32 v140, s83, v1
	s_mul_i32 s2, s90, 0x208800
	ds_read_b128 v[148:151], v140
	ds_read_b128 v[152:155], v140 offset:256
	ds_read_b128 v[156:159], v140 offset:8192
	ds_read_b128 v[160:163], v140 offset:8448
	v_add_u32_e32 v140, s84, v1
	s_cselect_b32 s5, s5, s43
	s_cselect_b32 s4, s4, s42
	s_add_u32 s2, s56, s2
	ds_read_b128 v[164:167], v140
	ds_read_b128 v[168:171], v140 offset:256
	ds_read_b128 v[172:175], v140 offset:8192
	ds_read_b128 v[176:179], v140 offset:8448
	s_addc_u32 s3, s57, 0
	s_add_u32 s22, s2, 0x411000
	s_addc_u32 s23, s3, 0
	s_and_b64 s[2:3], s[60:61], exec
	s_cselect_b32 s60, s22, s89
	s_cselect_b32 s61, s23, s35
	s_add_u32 s62, s60, 0x208800
	s_addc_u32 s63, s61, 0
	s_add_u32 s98, s60, s10
	s_addc_u32 s99, s61, s11
	s_add_u32 s100, s4, s14
	s_addc_u32 s101, s5, s15
	s_add_u32 s2, s20, 0x104080
	s_addc_u32 s3, s21, 0
	s_add_i32 m0, s36, 0xc000
	ds_read_b128 v[180:183], v145
	ds_read_b128 v[184:187], v145 offset:1024
	ds_read_b128 v[188:191], v145 offset:2048
	ds_read_b128 v[192:195], v145 offset:3072
	ds_read_b128 v[196:199], v145 offset:4096
	ds_read_b128 v[200:203], v145 offset:5120
	ds_read_b128 v[204:207], v145 offset:6144
	global_load_lds_dwordx4 v130, s[2:3]
	s_add_i32 m0, s36, 0xe000
	ds_read_b128 v[208:211], v145 offset:7168
	global_load_lds_dwordx4 v134, s[2:3]
	s_waitcnt vmcnt(8)
	s_waitcnt lgkmcnt(0)
	s_barrier
	v_mfma_f32_16x16x32_bf16 v[126:129], v[148:151], v[180:183], v[126:129]
	v_mfma_f32_16x16x32_bf16 v[122:125], v[152:155], v[180:183], v[122:125]
	v_mfma_f32_16x16x32_bf16 v[110:113], v[148:151], v[188:191], v[110:113]
	v_mfma_f32_16x16x32_bf16 v[106:109], v[152:155], v[188:191], v[106:109]
	v_mfma_f32_16x16x32_bf16 v[94:97], v[148:151], v[196:199], v[94:97]
	v_mfma_f32_16x16x32_bf16 v[90:93], v[152:155], v[196:199], v[90:93]
	v_mfma_f32_16x16x32_bf16 v[78:81], v[148:151], v[204:207], v[78:81]
	v_mfma_f32_16x16x32_bf16 v[74:77], v[152:155], v[204:207], v[74:77]
	v_mfma_f32_16x16x32_bf16 v[126:129], v[156:159], v[184:187], v[126:129]
	v_mfma_f32_16x16x32_bf16 v[122:125], v[160:163], v[184:187], v[122:125]
	v_mfma_f32_16x16x32_bf16 v[110:113], v[156:159], v[192:195], v[110:113]
	v_mfma_f32_16x16x32_bf16 v[106:109], v[160:163], v[192:195], v[106:109]
	v_mfma_f32_16x16x32_bf16 v[94:97], v[156:159], v[200:203], v[94:97]
	v_mfma_f32_16x16x32_bf16 v[90:93], v[160:163], v[200:203], v[90:93]
	v_mfma_f32_16x16x32_bf16 v[78:81], v[156:159], v[208:211], v[78:81]
	v_mfma_f32_16x16x32_bf16 v[74:77], v[160:163], v[208:211], v[74:77]
	v_mfma_f32_16x16x32_bf16 v[118:121], v[164:167], v[180:183], v[118:121]
	v_mfma_f32_16x16x32_bf16 v[114:117], v[168:171], v[180:183], v[114:117]
	v_mfma_f32_16x16x32_bf16 v[102:105], v[164:167], v[188:191], v[102:105]
	v_mfma_f32_16x16x32_bf16 v[98:101], v[168:171], v[188:191], v[98:101]
	v_mfma_f32_16x16x32_bf16 v[86:89], v[164:167], v[196:199], v[86:89]
	v_mfma_f32_16x16x32_bf16 v[82:85], v[168:171], v[196:199], v[82:85]
	v_mfma_f32_16x16x32_bf16 v[70:73], v[164:167], v[204:207], v[70:73]
	v_mfma_f32_16x16x32_bf16 v[66:69], v[168:171], v[204:207], v[66:69]
	v_mfma_f32_16x16x32_bf16 v[118:121], v[172:175], v[184:187], v[118:121]
	v_mfma_f32_16x16x32_bf16 v[114:117], v[176:179], v[184:187], v[114:117]
	v_mfma_f32_16x16x32_bf16 v[102:105], v[172:175], v[192:195], v[102:105]
	v_mfma_f32_16x16x32_bf16 v[98:101], v[176:179], v[192:195], v[98:101]
	v_mfma_f32_16x16x32_bf16 v[86:89], v[172:175], v[200:203], v[86:89]
	v_mfma_f32_16x16x32_bf16 v[82:85], v[176:179], v[200:203], v[82:85]
	v_mfma_f32_16x16x32_bf16 v[70:73], v[172:175], v[208:211], v[70:73]
	v_mfma_f32_16x16x32_bf16 v[66:69], v[176:179], v[208:211], v[66:69]
	s_barrier
	s_add_i32 s2, s83, s18
	s_mov_b32 m0, s2
	ds_read_b128 v[180:183], v145 offset:16384
	ds_read_b128 v[184:187], v145 offset:17408
	ds_read_b128 v[188:191], v145 offset:18432
	ds_read_b128 v[192:195], v145 offset:19456
	global_load_lds_dwordx4 v132, s[60:61]
	s_add_i32 m0, s2, 0x2000
	s_add_i32 s2, s84, s18
	global_load_lds_dwordx4 v136, s[60:61]
	s_mov_b32 m0, s2
	ds_read_b128 v[196:199], v145 offset:20480
	global_load_lds_dwordx4 v132, s[98:99]
	s_add_i32 m0, s2, 0x2000
	ds_read_b128 v[200:203], v145 offset:21504
	global_load_lds_dwordx4 v136, s[98:99]
	s_mov_b32 m0, s36
	ds_read_b128 v[204:207], v145 offset:22528
	global_load_lds_dwordx4 v130, s[4:5]
	s_mov_b32 m0, s37
	ds_read_b128 v[208:211], v145 offset:23552
	global_load_lds_dwordx4 v134, s[4:5]
	s_waitcnt vmcnt(8)
	s_waitcnt lgkmcnt(0)
	s_barrier
	v_mfma_f32_16x16x32_bf16 v[62:65], v[148:151], v[180:183], v[62:65]
	v_mfma_f32_16x16x32_bf16 v[58:61], v[152:155], v[180:183], v[58:61]
	v_mfma_f32_16x16x32_bf16 v[46:49], v[148:151], v[188:191], v[46:49]
	v_mfma_f32_16x16x32_bf16 v[42:45], v[152:155], v[188:191], v[42:45]
	v_mfma_f32_16x16x32_bf16 v[30:33], v[148:151], v[196:199], v[30:33]
	v_mfma_f32_16x16x32_bf16 v[26:29], v[152:155], v[196:199], v[26:29]
	v_mfma_f32_16x16x32_bf16 v[14:17], v[148:151], v[204:207], v[14:17]
	v_mfma_f32_16x16x32_bf16 v[10:13], v[152:155], v[204:207], v[10:13]
	v_mfma_f32_16x16x32_bf16 v[62:65], v[156:159], v[184:187], v[62:65]
	v_mfma_f32_16x16x32_bf16 v[58:61], v[160:163], v[184:187], v[58:61]
	v_mfma_f32_16x16x32_bf16 v[46:49], v[156:159], v[192:195], v[46:49]
	v_mfma_f32_16x16x32_bf16 v[42:45], v[160:163], v[192:195], v[42:45]
	v_mfma_f32_16x16x32_bf16 v[30:33], v[156:159], v[200:203], v[30:33]
	v_mfma_f32_16x16x32_bf16 v[26:29], v[160:163], v[200:203], v[26:29]
	v_mfma_f32_16x16x32_bf16 v[14:17], v[156:159], v[208:211], v[14:17]
	v_mfma_f32_16x16x32_bf16 v[10:13], v[160:163], v[208:211], v[10:13]
	v_mfma_f32_16x16x32_bf16 v[54:57], v[164:167], v[180:183], v[54:57]
	v_mfma_f32_16x16x32_bf16 v[50:53], v[168:171], v[180:183], v[50:53]
	v_mfma_f32_16x16x32_bf16 v[38:41], v[164:167], v[188:191], v[38:41]
	v_mfma_f32_16x16x32_bf16 v[34:37], v[168:171], v[188:191], v[34:37]
	v_mfma_f32_16x16x32_bf16 v[22:25], v[164:167], v[196:199], v[22:25]
	v_mfma_f32_16x16x32_bf16 v[18:21], v[168:171], v[196:199], v[18:21]
	v_mfma_f32_16x16x32_bf16 v[6:9], v[164:167], v[204:207], v[6:9]
	v_mfma_f32_16x16x32_bf16 v[2:5], v[168:171], v[204:207], v[2:5]
	v_mfma_f32_16x16x32_bf16 v[54:57], v[172:175], v[184:187], v[54:57]
	v_mfma_f32_16x16x32_bf16 v[50:53], v[176:179], v[184:187], v[50:53]
	v_mfma_f32_16x16x32_bf16 v[38:41], v[172:175], v[192:195], v[38:41]
	v_mfma_f32_16x16x32_bf16 v[34:37], v[176:179], v[192:195], v[34:37]
	v_mfma_f32_16x16x32_bf16 v[22:25], v[172:175], v[200:203], v[22:25]
	v_mfma_f32_16x16x32_bf16 v[18:21], v[176:179], v[200:203], v[18:21]
	v_mfma_f32_16x16x32_bf16 v[6:9], v[172:175], v[208:211], v[6:9]
	v_mfma_f32_16x16x32_bf16 v[2:5], v[176:179], v[208:211], v[2:5]
	s_barrier
	s_add_i32 s20, 0, 0x18000
	v_add_u32_e32 v147, s20, v1
	s_add_i32 s21, 0, 0x1c000
	ds_read_b128 v[148:151], v147
	ds_read_b128 v[152:155], v147 offset:256
	ds_read_b128 v[156:159], v147 offset:8192
	ds_read_b128 v[160:163], v147 offset:8448
	v_add_u32_e32 v147, s21, v1
	ds_read_b128 v[164:167], v147
	ds_read_b128 v[168:171], v147 offset:256
	ds_read_b128 v[172:175], v147 offset:8192
	ds_read_b128 v[176:179], v147 offset:8448
	s_add_u32 s2, s4, 0x104000
	s_addc_u32 s3, s5, 0
	s_mov_b32 m0, s41
	ds_read_b128 v[180:183], v145 offset:32768
	ds_read_b128 v[184:187], v145 offset:33792
	ds_read_b128 v[188:191], v145 offset:34816
	ds_read_b128 v[192:195], v145 offset:35840
	ds_read_b128 v[196:199], v145 offset:36864
	ds_read_b128 v[200:203], v145 offset:37888
	ds_read_b128 v[204:207], v145 offset:38912
	global_load_lds_dwordx4 v130, s[2:3]
	s_mov_b32 m0, s76
	ds_read_b128 v[208:211], v145 offset:39936
	global_load_lds_dwordx4 v134, s[2:3]
	s_waitcnt vmcnt(8)
	s_waitcnt lgkmcnt(0)
	s_barrier
	v_mfma_f32_16x16x32_bf16 v[126:129], v[148:151], v[180:183], v[126:129]
	v_mfma_f32_16x16x32_bf16 v[122:125], v[152:155], v[180:183], v[122:125]
	v_mfma_f32_16x16x32_bf16 v[110:113], v[148:151], v[188:191], v[110:113]
	v_mfma_f32_16x16x32_bf16 v[106:109], v[152:155], v[188:191], v[106:109]
	v_mfma_f32_16x16x32_bf16 v[94:97], v[148:151], v[196:199], v[94:97]
	v_mfma_f32_16x16x32_bf16 v[90:93], v[152:155], v[196:199], v[90:93]
	v_mfma_f32_16x16x32_bf16 v[78:81], v[148:151], v[204:207], v[78:81]
	v_mfma_f32_16x16x32_bf16 v[74:77], v[152:155], v[204:207], v[74:77]
	v_mfma_f32_16x16x32_bf16 v[126:129], v[156:159], v[184:187], v[126:129]
	v_mfma_f32_16x16x32_bf16 v[122:125], v[160:163], v[184:187], v[122:125]
	v_mfma_f32_16x16x32_bf16 v[110:113], v[156:159], v[192:195], v[110:113]
	v_mfma_f32_16x16x32_bf16 v[106:109], v[160:163], v[192:195], v[106:109]
	v_mfma_f32_16x16x32_bf16 v[94:97], v[156:159], v[200:203], v[94:97]
	v_mfma_f32_16x16x32_bf16 v[90:93], v[160:163], v[200:203], v[90:93]
	v_mfma_f32_16x16x32_bf16 v[78:81], v[156:159], v[208:211], v[78:81]
	v_mfma_f32_16x16x32_bf16 v[74:77], v[160:163], v[208:211], v[74:77]
	v_mfma_f32_16x16x32_bf16 v[118:121], v[164:167], v[180:183], v[118:121]
	v_mfma_f32_16x16x32_bf16 v[114:117], v[168:171], v[180:183], v[114:117]
	v_mfma_f32_16x16x32_bf16 v[102:105], v[164:167], v[188:191], v[102:105]
	v_mfma_f32_16x16x32_bf16 v[98:101], v[168:171], v[188:191], v[98:101]
	v_mfma_f32_16x16x32_bf16 v[86:89], v[164:167], v[196:199], v[86:89]
	v_mfma_f32_16x16x32_bf16 v[82:85], v[168:171], v[196:199], v[82:85]
	v_mfma_f32_16x16x32_bf16 v[70:73], v[164:167], v[204:207], v[70:73]
	v_mfma_f32_16x16x32_bf16 v[66:69], v[168:171], v[204:207], v[66:69]
	v_mfma_f32_16x16x32_bf16 v[118:121], v[172:175], v[184:187], v[118:121]
	v_mfma_f32_16x16x32_bf16 v[114:117], v[176:179], v[184:187], v[114:117]
	v_mfma_f32_16x16x32_bf16 v[102:105], v[172:175], v[192:195], v[102:105]
	v_mfma_f32_16x16x32_bf16 v[98:101], v[176:179], v[192:195], v[98:101]
	v_mfma_f32_16x16x32_bf16 v[86:89], v[172:175], v[200:203], v[86:89]
	v_mfma_f32_16x16x32_bf16 v[82:85], v[176:179], v[200:203], v[82:85]
	v_mfma_f32_16x16x32_bf16 v[70:73], v[172:175], v[208:211], v[70:73]
	v_mfma_f32_16x16x32_bf16 v[66:69], v[176:179], v[208:211], v[66:69]
	s_barrier
	s_add_i32 s2, s20, s18
	s_mov_b32 m0, s2
	ds_read_b128 v[180:183], v145 offset:49152
	ds_read_b128 v[184:187], v145 offset:50176
	ds_read_b128 v[188:191], v145 offset:51200
	ds_read_b128 v[192:195], v145 offset:52224
	global_load_lds_dwordx4 v132, s[62:63]
	s_add_i32 m0, s2, 0x2000
	s_add_u32 s2, s60, 0x209000
	s_addc_u32 s3, s61, 0
	s_add_i32 s4, s21, s18
	global_load_lds_dwordx4 v136, s[62:63]
	s_mov_b32 m0, s4
	ds_read_b128 v[196:199], v145 offset:53248
	global_load_lds_dwordx4 v132, s[2:3]
	s_add_i32 m0, s4, 0x2000
	ds_read_b128 v[200:203], v145 offset:54272
	global_load_lds_dwordx4 v136, s[2:3]
	s_mov_b32 m0, s77
	ds_read_b128 v[204:207], v145 offset:55296
	global_load_lds_dwordx4 v130, s[100:101]
	s_mov_b32 m0, s78
	ds_read_b128 v[208:211], v145 offset:56320
	global_load_lds_dwordx4 v134, s[100:101]
	s_waitcnt vmcnt(8)
	s_waitcnt lgkmcnt(0)
	s_barrier
	v_mfma_f32_16x16x32_bf16 v[62:65], v[148:151], v[180:183], v[62:65]
	v_mfma_f32_16x16x32_bf16 v[58:61], v[152:155], v[180:183], v[58:61]
	v_mfma_f32_16x16x32_bf16 v[46:49], v[148:151], v[188:191], v[46:49]
	v_mfma_f32_16x16x32_bf16 v[42:45], v[152:155], v[188:191], v[42:45]
	v_mfma_f32_16x16x32_bf16 v[30:33], v[148:151], v[196:199], v[30:33]
	v_mfma_f32_16x16x32_bf16 v[26:29], v[152:155], v[196:199], v[26:29]
	v_mfma_f32_16x16x32_bf16 v[14:17], v[148:151], v[204:207], v[14:17]
	v_mfma_f32_16x16x32_bf16 v[10:13], v[152:155], v[204:207], v[10:13]
	v_mfma_f32_16x16x32_bf16 v[62:65], v[156:159], v[184:187], v[62:65]
	v_mfma_f32_16x16x32_bf16 v[58:61], v[160:163], v[184:187], v[58:61]
	v_mfma_f32_16x16x32_bf16 v[46:49], v[156:159], v[192:195], v[46:49]
	v_mfma_f32_16x16x32_bf16 v[42:45], v[160:163], v[192:195], v[42:45]
	v_mfma_f32_16x16x32_bf16 v[30:33], v[156:159], v[200:203], v[30:33]
	v_mfma_f32_16x16x32_bf16 v[26:29], v[160:163], v[200:203], v[26:29]
	v_mfma_f32_16x16x32_bf16 v[14:17], v[156:159], v[208:211], v[14:17]
	v_mfma_f32_16x16x32_bf16 v[10:13], v[160:163], v[208:211], v[10:13]
	v_mfma_f32_16x16x32_bf16 v[54:57], v[164:167], v[180:183], v[54:57]
	v_mfma_f32_16x16x32_bf16 v[50:53], v[168:171], v[180:183], v[50:53]
	v_mfma_f32_16x16x32_bf16 v[38:41], v[164:167], v[188:191], v[38:41]
	v_mfma_f32_16x16x32_bf16 v[34:37], v[168:171], v[188:191], v[34:37]
	v_mfma_f32_16x16x32_bf16 v[22:25], v[164:167], v[196:199], v[22:25]
	v_mfma_f32_16x16x32_bf16 v[18:21], v[168:171], v[196:199], v[18:21]
	v_mfma_f32_16x16x32_bf16 v[6:9], v[164:167], v[204:207], v[6:9]
	v_mfma_f32_16x16x32_bf16 v[2:5], v[168:171], v[204:207], v[2:5]
	v_mfma_f32_16x16x32_bf16 v[54:57], v[172:175], v[184:187], v[54:57]
	v_mfma_f32_16x16x32_bf16 v[50:53], v[176:179], v[184:187], v[50:53]
	v_mfma_f32_16x16x32_bf16 v[38:41], v[172:175], v[192:195], v[38:41]
	v_mfma_f32_16x16x32_bf16 v[34:37], v[176:179], v[192:195], v[34:37]
	v_mfma_f32_16x16x32_bf16 v[22:25], v[172:175], v[200:203], v[22:25]
	v_mfma_f32_16x16x32_bf16 v[18:21], v[176:179], v[200:203], v[18:21]
	v_mfma_f32_16x16x32_bf16 v[6:9], v[172:175], v[208:211], v[6:9]
	v_mfma_f32_16x16x32_bf16 v[2:5], v[176:179], v[208:211], v[2:5]
	s_barrier
	s_add_i32 s2, s90, 2
	s_cmp_gt_u32 s90, 61
	s_cbranch_scc1 .LBB0_802
	s_mov_b32 s90, s2
	s_branch .LBB0_767

.LBB0_933:
	s_lshl_b32 s2, s88, 7
	s_add_u32 s26, s34, s2
	s_addc_u32 s27, s35, 0
	s_add_u32 s46, s26, 0x100
	s_addc_u32 s47, s27, 0
	s_and_b64 s[2:3], s[44:45], exec
	v_add_u32_e32 v187, s36, v182
	s_mul_i32 s2, s88, 0x88800
	ds_read_b128 v[128:131], v187
	ds_read_b128 v[132:135], v187 offset:256
	ds_read_b128 v[178:181], v187 offset:8192
	ds_read_b128 v[188:191], v187 offset:8448
	v_add_u32_e32 v187, s37, v182
	s_cselect_b32 s51, s47, s23
	s_cselect_b32 s50, s46, s22
	s_add_u32 s2, s40, s2
	ds_read_b128 v[192:195], v187
	ds_read_b128 v[196:199], v187 offset:256
	ds_read_b128 v[200:203], v187 offset:8192
	ds_read_b128 v[204:207], v187 offset:8448
	s_addc_u32 s3, s41, 0
	s_add_u32 s46, s2, 0x111000
	s_addc_u32 s47, s3, 0
	s_and_b64 s[2:3], s[44:45], exec
	s_cselect_b32 s44, s46, s87
	s_cselect_b32 s45, s47, s21
	s_add_u32 s46, s44, 0x88800
	s_addc_u32 s47, s45, 0
	s_add_u32 s2, s26, 0x404080
	s_addc_u32 s3, s27, 0
	s_add_u32 s98, s44, s4
	s_addc_u32 s99, s45, s5
	s_add_u32 s100, s50, s12
	s_addc_u32 s101, s51, s13
	s_add_i32 m0, s33, 0xc000
	ds_read_b128 v[208:211], v185
	ds_read_b128 v[212:215], v185 offset:1024
	ds_read_b128 v[216:219], v185 offset:2048
	ds_read_b128 v[220:223], v185 offset:3072
	ds_read_b128 v[224:227], v185 offset:4096
	ds_read_b128 v[228:231], v185 offset:5120
	ds_read_b128 v[232:235], v185 offset:6144
	global_load_lds_dwordx4 v136, s[2:3]
	s_add_i32 m0, s33, 0xe000
	ds_read_b128 v[236:239], v185 offset:7168
	global_load_lds_dwordx4 v140, s[2:3]
	s_waitcnt vmcnt(8)
	s_waitcnt lgkmcnt(0)
	s_barrier
	v_mfma_f32_16x16x32_bf16 v[124:127], v[128:131], v[208:211], v[124:127]
	v_mfma_f32_16x16x32_bf16 v[120:123], v[132:135], v[208:211], v[120:123]
	v_mfma_f32_16x16x32_bf16 v[108:111], v[128:131], v[216:219], v[108:111]
	v_mfma_f32_16x16x32_bf16 v[104:107], v[132:135], v[216:219], v[104:107]
	v_mfma_f32_16x16x32_bf16 v[92:95], v[128:131], v[224:227], v[92:95]
	v_mfma_f32_16x16x32_bf16 v[88:91], v[132:135], v[224:227], v[88:91]
	v_mfma_f32_16x16x32_bf16 v[76:79], v[128:131], v[232:235], v[76:79]
	v_mfma_f32_16x16x32_bf16 v[72:75], v[132:135], v[232:235], v[72:75]
	v_mfma_f32_16x16x32_bf16 v[124:127], v[178:181], v[212:215], v[124:127]
	v_mfma_f32_16x16x32_bf16 v[120:123], v[188:191], v[212:215], v[120:123]
	v_mfma_f32_16x16x32_bf16 v[108:111], v[178:181], v[220:223], v[108:111]
	v_mfma_f32_16x16x32_bf16 v[104:107], v[188:191], v[220:223], v[104:107]
	v_mfma_f32_16x16x32_bf16 v[92:95], v[178:181], v[228:231], v[92:95]
	v_mfma_f32_16x16x32_bf16 v[88:91], v[188:191], v[228:231], v[88:91]
	v_mfma_f32_16x16x32_bf16 v[76:79], v[178:181], v[236:239], v[76:79]
	v_mfma_f32_16x16x32_bf16 v[72:75], v[188:191], v[236:239], v[72:75]
	v_mfma_f32_16x16x32_bf16 v[116:119], v[192:195], v[208:211], v[116:119]
	v_mfma_f32_16x16x32_bf16 v[112:115], v[196:199], v[208:211], v[112:115]
	v_mfma_f32_16x16x32_bf16 v[100:103], v[192:195], v[216:219], v[100:103]
	v_mfma_f32_16x16x32_bf16 v[96:99], v[196:199], v[216:219], v[96:99]
	v_mfma_f32_16x16x32_bf16 v[84:87], v[192:195], v[224:227], v[84:87]
	v_mfma_f32_16x16x32_bf16 v[80:83], v[196:199], v[224:227], v[80:83]
	v_mfma_f32_16x16x32_bf16 v[68:71], v[192:195], v[232:235], v[68:71]
	v_mfma_f32_16x16x32_bf16 v[64:67], v[196:199], v[232:235], v[64:67]
	v_mfma_f32_16x16x32_bf16 v[116:119], v[200:203], v[212:215], v[116:119]
	v_mfma_f32_16x16x32_bf16 v[112:115], v[204:207], v[212:215], v[112:115]
	v_mfma_f32_16x16x32_bf16 v[100:103], v[200:203], v[220:223], v[100:103]
	v_mfma_f32_16x16x32_bf16 v[96:99], v[204:207], v[220:223], v[96:99]
	v_mfma_f32_16x16x32_bf16 v[84:87], v[200:203], v[228:231], v[84:87]
	v_mfma_f32_16x16x32_bf16 v[80:83], v[204:207], v[228:231], v[80:83]
	v_mfma_f32_16x16x32_bf16 v[68:71], v[200:203], v[236:239], v[68:71]
	v_mfma_f32_16x16x32_bf16 v[64:67], v[204:207], v[236:239], v[64:67]
	s_barrier
	s_add_i32 s2, s36, s31
	s_mov_b32 m0, s2
	ds_read_b128 v[208:211], v185 offset:16384
	ds_read_b128 v[212:215], v185 offset:17408
	ds_read_b128 v[216:219], v185 offset:18432
	ds_read_b128 v[220:223], v185 offset:19456
	global_load_lds_dwordx4 v138, s[44:45]
	s_add_i32 m0, s2, 0x2000
	s_add_i32 s2, s37, s31
	global_load_lds_dwordx4 v142, s[44:45]
	s_mov_b32 m0, s2
	ds_read_b128 v[224:227], v185 offset:20480
	global_load_lds_dwordx4 v138, s[98:99]
	s_add_i32 m0, s2, 0x2000
	ds_read_b128 v[228:231], v185 offset:21504
	global_load_lds_dwordx4 v142, s[98:99]
	s_mov_b32 m0, s33
	ds_read_b128 v[232:235], v185 offset:22528
	global_load_lds_dwordx4 v136, s[50:51]
	s_mov_b32 m0, s72
	ds_read_b128 v[236:239], v185 offset:23552
	global_load_lds_dwordx4 v140, s[50:51]
	s_waitcnt vmcnt(8)
	s_waitcnt lgkmcnt(0)
	s_barrier
	v_mfma_f32_16x16x32_bf16 v[60:63], v[128:131], v[208:211], v[60:63]
	v_mfma_f32_16x16x32_bf16 v[56:59], v[132:135], v[208:211], v[56:59]
	v_mfma_f32_16x16x32_bf16 v[44:47], v[128:131], v[216:219], v[44:47]
	v_mfma_f32_16x16x32_bf16 v[40:43], v[132:135], v[216:219], v[40:43]
	v_mfma_f32_16x16x32_bf16 v[28:31], v[128:131], v[224:227], v[28:31]
	v_mfma_f32_16x16x32_bf16 v[24:27], v[132:135], v[224:227], v[24:27]
	v_mfma_f32_16x16x32_bf16 v[12:15], v[128:131], v[232:235], v[12:15]
	v_mfma_f32_16x16x32_bf16 v[8:11], v[132:135], v[232:235], v[8:11]
	v_mfma_f32_16x16x32_bf16 v[60:63], v[178:181], v[212:215], v[60:63]
	v_mfma_f32_16x16x32_bf16 v[56:59], v[188:191], v[212:215], v[56:59]
	v_mfma_f32_16x16x32_bf16 v[44:47], v[178:181], v[220:223], v[44:47]
	v_mfma_f32_16x16x32_bf16 v[40:43], v[188:191], v[220:223], v[40:43]
	v_mfma_f32_16x16x32_bf16 v[28:31], v[178:181], v[228:231], v[28:31]
	v_mfma_f32_16x16x32_bf16 v[24:27], v[188:191], v[228:231], v[24:27]
	v_mfma_f32_16x16x32_bf16 v[12:15], v[178:181], v[236:239], v[12:15]
	v_mfma_f32_16x16x32_bf16 v[8:11], v[188:191], v[236:239], v[8:11]
	v_mfma_f32_16x16x32_bf16 v[52:55], v[192:195], v[208:211], v[52:55]
	v_mfma_f32_16x16x32_bf16 v[48:51], v[196:199], v[208:211], v[48:51]
	v_mfma_f32_16x16x32_bf16 v[36:39], v[192:195], v[216:219], v[36:39]
	v_mfma_f32_16x16x32_bf16 v[32:35], v[196:199], v[216:219], v[32:35]
	v_mfma_f32_16x16x32_bf16 v[20:23], v[192:195], v[224:227], v[20:23]
	v_mfma_f32_16x16x32_bf16 v[16:19], v[196:199], v[224:227], v[16:19]
	v_mfma_f32_16x16x32_bf16 v[4:7], v[192:195], v[232:235], v[4:7]
	v_mfma_f32_16x16x32_bf16 v[0:3], v[196:199], v[232:235], v[0:3]
	v_mfma_f32_16x16x32_bf16 v[52:55], v[200:203], v[212:215], v[52:55]
	v_mfma_f32_16x16x32_bf16 v[48:51], v[204:207], v[212:215], v[48:51]
	v_mfma_f32_16x16x32_bf16 v[36:39], v[200:203], v[220:223], v[36:39]
	v_mfma_f32_16x16x32_bf16 v[32:35], v[204:207], v[220:223], v[32:35]
	v_mfma_f32_16x16x32_bf16 v[20:23], v[200:203], v[228:231], v[20:23]
	v_mfma_f32_16x16x32_bf16 v[16:19], v[204:207], v[228:231], v[16:19]
	v_mfma_f32_16x16x32_bf16 v[4:7], v[200:203], v[236:239], v[4:7]
	v_mfma_f32_16x16x32_bf16 v[0:3], v[204:207], v[236:239], v[0:3]
	s_barrier
	s_add_i32 s26, 0, 0x18000
	v_add_u32_e32 v187, s26, v182
	s_add_i32 s27, 0, 0x1c000
	ds_read_b128 v[128:131], v187
	ds_read_b128 v[132:135], v187 offset:256
	ds_read_b128 v[178:181], v187 offset:8192
	ds_read_b128 v[188:191], v187 offset:8448
	v_add_u32_e32 v187, s27, v182
	ds_read_b128 v[192:195], v187
	ds_read_b128 v[196:199], v187 offset:256
	ds_read_b128 v[200:203], v187 offset:8192
	ds_read_b128 v[204:207], v187 offset:8448
	s_add_u32 s2, s50, 0x404000
	s_addc_u32 s3, s51, 0
	s_mov_b32 m0, s73
	ds_read_b128 v[208:211], v185 offset:32768
	ds_read_b128 v[212:215], v185 offset:33792
	ds_read_b128 v[216:219], v185 offset:34816
	ds_read_b128 v[220:223], v185 offset:35840
	ds_read_b128 v[224:227], v185 offset:36864
	ds_read_b128 v[228:231], v185 offset:37888
	ds_read_b128 v[232:235], v185 offset:38912
	global_load_lds_dwordx4 v136, s[2:3]
	s_mov_b32 m0, s74
	ds_read_b128 v[236:239], v185 offset:39936
	global_load_lds_dwordx4 v140, s[2:3]
	s_waitcnt vmcnt(8)
	s_waitcnt lgkmcnt(0)
	s_barrier
	v_mfma_f32_16x16x32_bf16 v[124:127], v[128:131], v[208:211], v[124:127]
	v_mfma_f32_16x16x32_bf16 v[120:123], v[132:135], v[208:211], v[120:123]
	v_mfma_f32_16x16x32_bf16 v[108:111], v[128:131], v[216:219], v[108:111]
	v_mfma_f32_16x16x32_bf16 v[104:107], v[132:135], v[216:219], v[104:107]
	v_mfma_f32_16x16x32_bf16 v[92:95], v[128:131], v[224:227], v[92:95]
	v_mfma_f32_16x16x32_bf16 v[88:91], v[132:135], v[224:227], v[88:91]
	v_mfma_f32_16x16x32_bf16 v[76:79], v[128:131], v[232:235], v[76:79]
	v_mfma_f32_16x16x32_bf16 v[72:75], v[132:135], v[232:235], v[72:75]
	v_mfma_f32_16x16x32_bf16 v[124:127], v[178:181], v[212:215], v[124:127]
	v_mfma_f32_16x16x32_bf16 v[120:123], v[188:191], v[212:215], v[120:123]
	v_mfma_f32_16x16x32_bf16 v[108:111], v[178:181], v[220:223], v[108:111]
	v_mfma_f32_16x16x32_bf16 v[104:107], v[188:191], v[220:223], v[104:107]
	v_mfma_f32_16x16x32_bf16 v[92:95], v[178:181], v[228:231], v[92:95]
	v_mfma_f32_16x16x32_bf16 v[88:91], v[188:191], v[228:231], v[88:91]
	v_mfma_f32_16x16x32_bf16 v[76:79], v[178:181], v[236:239], v[76:79]
	v_mfma_f32_16x16x32_bf16 v[72:75], v[188:191], v[236:239], v[72:75]
	v_mfma_f32_16x16x32_bf16 v[116:119], v[192:195], v[208:211], v[116:119]
	v_mfma_f32_16x16x32_bf16 v[112:115], v[196:199], v[208:211], v[112:115]
	v_mfma_f32_16x16x32_bf16 v[100:103], v[192:195], v[216:219], v[100:103]
	v_mfma_f32_16x16x32_bf16 v[96:99], v[196:199], v[216:219], v[96:99]
	v_mfma_f32_16x16x32_bf16 v[84:87], v[192:195], v[224:227], v[84:87]
	v_mfma_f32_16x16x32_bf16 v[80:83], v[196:199], v[224:227], v[80:83]
	v_mfma_f32_16x16x32_bf16 v[68:71], v[192:195], v[232:235], v[68:71]
	v_mfma_f32_16x16x32_bf16 v[64:67], v[196:199], v[232:235], v[64:67]
	v_mfma_f32_16x16x32_bf16 v[116:119], v[200:203], v[212:215], v[116:119]
	v_mfma_f32_16x16x32_bf16 v[112:115], v[204:207], v[212:215], v[112:115]
	v_mfma_f32_16x16x32_bf16 v[100:103], v[200:203], v[220:223], v[100:103]
	v_mfma_f32_16x16x32_bf16 v[96:99], v[204:207], v[220:223], v[96:99]
	v_mfma_f32_16x16x32_bf16 v[84:87], v[200:203], v[228:231], v[84:87]
	v_mfma_f32_16x16x32_bf16 v[80:83], v[204:207], v[228:231], v[80:83]
	v_mfma_f32_16x16x32_bf16 v[68:71], v[200:203], v[236:239], v[68:71]
	v_mfma_f32_16x16x32_bf16 v[64:67], v[204:207], v[236:239], v[64:67]
	s_barrier
	s_add_i32 s2, s26, s31
	s_mov_b32 m0, s2
	ds_read_b128 v[208:211], v185 offset:49152
	ds_read_b128 v[212:215], v185 offset:50176
	ds_read_b128 v[216:219], v185 offset:51200
	ds_read_b128 v[220:223], v185 offset:52224
	global_load_lds_dwordx4 v138, s[46:47]
	s_add_i32 m0, s2, 0x2000
	s_add_u32 s2, s44, 0x89000
	s_addc_u32 s3, s45, 0
	s_add_i32 s26, s27, s31
	global_load_lds_dwordx4 v142, s[46:47]
	s_mov_b32 m0, s26
	ds_read_b128 v[224:227], v185 offset:53248
	global_load_lds_dwordx4 v138, s[2:3]
	s_add_i32 m0, s26, 0x2000
	ds_read_b128 v[228:231], v185 offset:54272
	global_load_lds_dwordx4 v142, s[2:3]
	s_mov_b32 m0, s78
	ds_read_b128 v[232:235], v185 offset:55296
	global_load_lds_dwordx4 v136, s[100:101]
	s_mov_b32 m0, s79
	ds_read_b128 v[236:239], v185 offset:56320
	global_load_lds_dwordx4 v140, s[100:101]
	s_waitcnt vmcnt(8)
	s_waitcnt lgkmcnt(0)
	s_barrier
	v_mfma_f32_16x16x32_bf16 v[60:63], v[128:131], v[208:211], v[60:63]
	v_mfma_f32_16x16x32_bf16 v[56:59], v[132:135], v[208:211], v[56:59]
	v_mfma_f32_16x16x32_bf16 v[44:47], v[128:131], v[216:219], v[44:47]
	v_mfma_f32_16x16x32_bf16 v[40:43], v[132:135], v[216:219], v[40:43]
	v_mfma_f32_16x16x32_bf16 v[28:31], v[128:131], v[224:227], v[28:31]
	v_mfma_f32_16x16x32_bf16 v[24:27], v[132:135], v[224:227], v[24:27]
	v_mfma_f32_16x16x32_bf16 v[12:15], v[128:131], v[232:235], v[12:15]
	v_mfma_f32_16x16x32_bf16 v[8:11], v[132:135], v[232:235], v[8:11]
	v_mfma_f32_16x16x32_bf16 v[60:63], v[178:181], v[212:215], v[60:63]
	v_mfma_f32_16x16x32_bf16 v[56:59], v[188:191], v[212:215], v[56:59]
	v_mfma_f32_16x16x32_bf16 v[44:47], v[178:181], v[220:223], v[44:47]
	v_mfma_f32_16x16x32_bf16 v[40:43], v[188:191], v[220:223], v[40:43]
	v_mfma_f32_16x16x32_bf16 v[28:31], v[178:181], v[228:231], v[28:31]
	v_mfma_f32_16x16x32_bf16 v[24:27], v[188:191], v[228:231], v[24:27]
	v_mfma_f32_16x16x32_bf16 v[12:15], v[178:181], v[236:239], v[12:15]
	v_mfma_f32_16x16x32_bf16 v[8:11], v[188:191], v[236:239], v[8:11]
	v_mfma_f32_16x16x32_bf16 v[52:55], v[192:195], v[208:211], v[52:55]
	v_mfma_f32_16x16x32_bf16 v[48:51], v[196:199], v[208:211], v[48:51]
	v_mfma_f32_16x16x32_bf16 v[36:39], v[192:195], v[216:219], v[36:39]
	v_mfma_f32_16x16x32_bf16 v[32:35], v[196:199], v[216:219], v[32:35]
	v_mfma_f32_16x16x32_bf16 v[20:23], v[192:195], v[224:227], v[20:23]
	v_mfma_f32_16x16x32_bf16 v[16:19], v[196:199], v[224:227], v[16:19]
	v_mfma_f32_16x16x32_bf16 v[4:7], v[192:195], v[232:235], v[4:7]
	v_mfma_f32_16x16x32_bf16 v[0:3], v[196:199], v[232:235], v[0:3]
	v_mfma_f32_16x16x32_bf16 v[52:55], v[200:203], v[212:215], v[52:55]
	v_mfma_f32_16x16x32_bf16 v[48:51], v[204:207], v[212:215], v[48:51]
	v_mfma_f32_16x16x32_bf16 v[36:39], v[200:203], v[220:223], v[36:39]
	v_mfma_f32_16x16x32_bf16 v[32:35], v[204:207], v[220:223], v[32:35]
	v_mfma_f32_16x16x32_bf16 v[20:23], v[200:203], v[228:231], v[20:23]
	v_mfma_f32_16x16x32_bf16 v[16:19], v[204:207], v[228:231], v[16:19]
	v_mfma_f32_16x16x32_bf16 v[4:7], v[200:203], v[236:239], v[4:7]
	v_mfma_f32_16x16x32_bf16 v[0:3], v[204:207], v[236:239], v[0:3]
	s_barrier
	s_add_i32 s2, s88, 2
	s_cmpk_gt_u32 s88, 0xfd
	s_cbranch_scc1 .LBB0_939
	s_mov_b32 s88, s2
	s_branch .LBB0_904
